# scan patch + K-loop heads re-phased: in-proj 0 mod 8, others 4 mod 8
# baseline (speedup 1.0000x reference)
.LBB0_131:
	s_ashr_i32 s25, s24, 31
	s_lshl_b64 s[26:27], s[24:25], 21
	s_add_u32 s26, s46, s26
	s_addc_u32 s27, s47, s27
	s_and_b64 s[28:29], s[44:45], exec
	s_cselect_b32 s25, s27, s35
	s_cselect_b32 s61, s26, s34
	s_ashr_i32 s23, s22, 31
	s_lshl_b64 s[28:29], s[22:23], 21
	s_add_u32 s28, s48, s28
	s_addc_u32 s29, s49, s29
	s_and_b64 s[40:41], s[44:45], exec
	s_cselect_b32 s23, s29, s37
	s_cselect_b32 s62, s28, s36
	s_add_u32 s34, s34, 0x100080
	s_addc_u32 s35, s35, 0
	s_add_u32 s63, s36, 0x100
	v_mov_b32_e32 v42, 0
	s_addc_u32 s66, s37, 0
	s_mov_b32 s67, -2
	v_mov_b32_e32 v43, v42
	v_mov_b32_e32 v44, v42
	v_mov_b32_e32 v45, v42
	v_mov_b32_e32 v46, v42
	v_mov_b32_e32 v47, v42
	v_mov_b32_e32 v48, v42
	v_mov_b32_e32 v49, v42
	v_mov_b32_e32 v58, v42
	v_mov_b32_e32 v59, v42
	v_mov_b32_e32 v60, v42
	v_mov_b32_e32 v61, v42
	v_mov_b32_e32 v66, v42
	v_mov_b32_e32 v67, v42
	v_mov_b32_e32 v68, v42
	v_mov_b32_e32 v69, v42
	s_waitcnt vmcnt(0)
	v_mov_b32_e32 v78, v42
	v_mov_b32_e32 v79, v42
	v_mov_b32_e32 v80, v42
	v_mov_b32_e32 v81, v42
	v_mov_b32_e32 v86, v42
	v_mov_b32_e32 v87, v42
	v_mov_b32_e32 v88, v42
	v_mov_b32_e32 v89, v42
	v_mov_b32_e32 v90, v42
	v_mov_b32_e32 v91, v42
	v_mov_b32_e32 v92, v42
	v_mov_b32_e32 v93, v42
	v_mov_b32_e32 v94, v42
	v_mov_b32_e32 v95, v42
	v_mov_b32_e32 v96, v42
	v_mov_b32_e32 v97, v42
	v_mov_b32_e32 v2, v42
	v_mov_b32_e32 v3, v42
	v_mov_b32_e32 v4, v42
	v_mov_b32_e32 v5, v42
	v_mov_b32_e32 v6, v42
	v_mov_b32_e32 v7, v42
	v_mov_b32_e32 v8, v42
	v_mov_b32_e32 v9, v42
	v_mov_b32_e32 v10, v42
	v_mov_b32_e32 v11, v42
	v_mov_b32_e32 v12, v42
	v_mov_b32_e32 v13, v42
	v_mov_b32_e32 v14, v42
	v_mov_b32_e32 v15, v42
	v_mov_b32_e32 v16, v42
	v_mov_b32_e32 v17, v42
	v_mov_b32_e32 v18, v42
	v_mov_b32_e32 v19, v42
	s_waitcnt vmcnt(0)
	v_mov_b32_e32 v20, v42
	v_mov_b32_e32 v21, v42
	v_mov_b32_e32 v22, v42
	v_mov_b32_e32 v23, v42
	v_mov_b32_e32 v24, v42
	v_mov_b32_e32 v25, v42
	v_mov_b32_e32 v26, v42
	v_mov_b32_e32 v27, v42
	v_mov_b32_e32 v28, v42
	v_mov_b32_e32 v29, v42
	v_mov_b32_e32 v30, v42
	v_mov_b32_e32 v31, v42
	v_mov_b32_e32 v32, v42
	v_mov_b32_e32 v33, v42
	v_mov_b32_e32 v98, v42
	v_mov_b32_e32 v99, v42
	v_mov_b32_e32 v100, v42
	v_mov_b32_e32 v101, v42
	v_mov_b32_e32 v102, v42
	v_mov_b32_e32 v103, v42
	v_mov_b32_e32 v104, v42
	v_mov_b32_e32 v105, v42
	v_mov_b32_e32 v106, v42
	v_mov_b32_e32 v107, v42
	v_mov_b32_e32 v108, v42
	v_mov_b32_e32 v109, v42
	v_mov_b32_e32 v110, v42
	v_mov_b32_e32 v111, v42
	v_mov_b32_e32 v112, v42
	v_mov_b32_e32 v113, v42
	v_mov_b32_e32 v114, v42
	v_mov_b32_e32 v115, v42
	v_mov_b32_e32 v116, v42
	v_mov_b32_e32 v117, v42
	v_mov_b32_e32 v118, v42
	v_mov_b32_e32 v119, v42
	v_mov_b32_e32 v120, v42
	v_mov_b32_e32 v121, v42
	v_mov_b32_e32 v122, v42
	v_mov_b32_e32 v123, v42
	v_mov_b32_e32 v124, v42
	v_mov_b32_e32 v125, v42
	v_mov_b32_e32 v126, v42
	v_mov_b32_e32 v127, v42
	v_mov_b32_e32 v128, v42
	v_mov_b32_e32 v129, v42
	v_mov_b32_e32 v34, v42
	v_mov_b32_e32 v35, v42
	v_mov_b32_e32 v36, v42
	v_mov_b32_e32 v37, v42
	v_mov_b32_e32 v38, v42
	v_mov_b32_e32 v39, v42
	v_mov_b32_e32 v40, v42
	v_mov_b32_e32 v41, v42
	v_mov_b32_e32 v50, v42
	v_mov_b32_e32 v51, v42
	v_mov_b32_e32 v52, v42
	v_mov_b32_e32 v53, v42
	v_mov_b32_e32 v54, v42
	v_mov_b32_e32 v55, v42
	v_mov_b32_e32 v56, v42
	v_mov_b32_e32 v57, v42
	v_mov_b32_e32 v62, v42
	v_mov_b32_e32 v63, v42
	v_mov_b32_e32 v64, v42
	v_mov_b32_e32 v65, v42
	v_mov_b32_e32 v70, v42
	v_mov_b32_e32 v71, v42
	v_mov_b32_e32 v72, v42
	v_mov_b32_e32 v73, v42
	v_mov_b32_e32 v74, v42
	v_mov_b32_e32 v75, v42
	v_mov_b32_e32 v76, v42
	v_mov_b32_e32 v77, v42
	v_mov_b32_e32 v82, v42
	v_mov_b32_e32 v83, v42
	v_mov_b32_e32 v84, v42
	v_mov_b32_e32 v85, v42
	s_nop 0

.LBB0_1404:
	s_add_u32 s51, s22, 0x100
	v_mov_b32_e32 v2, 0
	s_addc_u32 s52, s23, 0
	s_mov_b32 s53, -2
	v_mov_b32_e32 v3, v2
	v_mov_b32_e32 v4, v2
	s_waitcnt lgkmcnt(0)
	v_mov_b32_e32 v5, v2
	v_mov_b32_e32 v6, v2
	v_mov_b32_e32 v7, v2
	v_mov_b32_e32 v8, v2
	v_mov_b32_e32 v9, v2
	v_mov_b32_e32 v18, v2
	v_mov_b32_e32 v19, v2
	v_mov_b32_e32 v20, v2
	v_mov_b32_e32 v21, v2
	v_mov_b32_e32 v22, v2
	v_mov_b32_e32 v23, v2
	v_mov_b32_e32 v24, v2
	v_mov_b32_e32 v25, v2
	s_waitcnt vmcnt(0)
	v_mov_b32_e32 v34, v2
	v_mov_b32_e32 v35, v2
	v_mov_b32_e32 v36, v2
	v_mov_b32_e32 v37, v2
	v_mov_b32_e32 v38, v2
	v_mov_b32_e32 v39, v2
	v_mov_b32_e32 v40, v2
	v_mov_b32_e32 v41, v2
	v_mov_b32_e32 v50, v2
	v_mov_b32_e32 v51, v2
	v_mov_b32_e32 v52, v2
	v_mov_b32_e32 v53, v2
	v_mov_b32_e32 v54, v2
	v_mov_b32_e32 v55, v2
	v_mov_b32_e32 v56, v2
	v_mov_b32_e32 v57, v2
	v_mov_b32_e32 v10, v2
	v_mov_b32_e32 v11, v2
	v_mov_b32_e32 v12, v2
	v_mov_b32_e32 v13, v2
	v_mov_b32_e32 v14, v2
	v_mov_b32_e32 v15, v2
	v_mov_b32_e32 v16, v2
	v_mov_b32_e32 v17, v2
	v_mov_b32_e32 v26, v2
	v_mov_b32_e32 v27, v2
	v_mov_b32_e32 v28, v2
	v_mov_b32_e32 v29, v2
	v_mov_b32_e32 v30, v2
	v_mov_b32_e32 v31, v2
	v_mov_b32_e32 v32, v2
	v_mov_b32_e32 v33, v2
	v_mov_b32_e32 v42, v2
	v_mov_b32_e32 v43, v2
	v_mov_b32_e32 v44, v2
	v_mov_b32_e32 v45, v2
	v_mov_b32_e32 v46, v2
	v_mov_b32_e32 v47, v2
	v_mov_b32_e32 v48, v2
	v_mov_b32_e32 v49, v2
	v_mov_b32_e32 v58, v2
	v_mov_b32_e32 v59, v2
	v_mov_b32_e32 v60, v2
	v_mov_b32_e32 v61, v2
	v_mov_b32_e32 v62, v2
	v_mov_b32_e32 v63, v2
	v_mov_b32_e32 v64, v2
	v_mov_b32_e32 v65, v2
	v_mov_b32_e32 v66, v2
	v_mov_b32_e32 v67, v2
	v_mov_b32_e32 v68, v2
	v_mov_b32_e32 v69, v2
	v_mov_b32_e32 v70, v2
	v_mov_b32_e32 v71, v2
	v_mov_b32_e32 v72, v2
	v_mov_b32_e32 v73, v2
	v_mov_b32_e32 v82, v2
	v_mov_b32_e32 v83, v2
	v_mov_b32_e32 v84, v2
	v_mov_b32_e32 v85, v2
	v_mov_b32_e32 v86, v2
	v_mov_b32_e32 v87, v2
	v_mov_b32_e32 v88, v2
	v_mov_b32_e32 v89, v2
	v_mov_b32_e32 v98, v2
	v_mov_b32_e32 v99, v2
	v_mov_b32_e32 v100, v2
	v_mov_b32_e32 v101, v2
	v_mov_b32_e32 v102, v2
	v_mov_b32_e32 v103, v2
	v_mov_b32_e32 v104, v2
	v_mov_b32_e32 v105, v2
	v_mov_b32_e32 v114, v2
	v_mov_b32_e32 v115, v2
	v_mov_b32_e32 v116, v2
	v_mov_b32_e32 v117, v2
	v_mov_b32_e32 v118, v2
	v_mov_b32_e32 v119, v2
	v_mov_b32_e32 v120, v2
	v_mov_b32_e32 v121, v2
	v_mov_b32_e32 v74, v2
	v_mov_b32_e32 v75, v2
	v_mov_b32_e32 v76, v2
	v_mov_b32_e32 v77, v2
	v_mov_b32_e32 v78, v2
	v_mov_b32_e32 v79, v2
	v_mov_b32_e32 v80, v2
	v_mov_b32_e32 v81, v2
	v_mov_b32_e32 v90, v2
	v_mov_b32_e32 v91, v2
	v_mov_b32_e32 v92, v2
	v_mov_b32_e32 v93, v2
	v_mov_b32_e32 v94, v2
	v_mov_b32_e32 v95, v2
	v_mov_b32_e32 v96, v2
	v_mov_b32_e32 v97, v2
	v_mov_b32_e32 v106, v2
	v_mov_b32_e32 v107, v2
	v_mov_b32_e32 v108, v2
	v_mov_b32_e32 v109, v2
	v_mov_b32_e32 v110, v2
	v_mov_b32_e32 v111, v2
	v_mov_b32_e32 v112, v2
	v_mov_b32_e32 v113, v2
	v_mov_b32_e32 v122, v2
	v_mov_b32_e32 v123, v2
	v_mov_b32_e32 v124, v2
	v_mov_b32_e32 v125, v2
	v_mov_b32_e32 v126, v2
	v_mov_b32_e32 v127, v2
	v_mov_b32_e32 v128, v2
	v_mov_b32_e32 v129, v2
	s_nop 0
